# seams 1-5: one-hop arrive (atomic add without return on group word), eight lanes poll the eight group words; on top of P0 fast path + nt loads + scalar tile byte
# baseline (speedup 1.0000x reference)
; __device__ __forceinline__ void own_barrier(unsigned* cnt, unsigned G) {
;     asm volatile("s_waitcnt vmcnt(0) lgkmcnt(0)" ::: "memory");
;     __syncthreads();
;     if (threadIdx.x == 0) {
;         __builtin_amdgcn_fence(__ATOMIC_RELEASE, "agent"); asm volatile("s_waitcnt vmcnt(0)" ::: "memory");
;         unsigned target;
;         if ((G & 7u) == 0u) { target = 8u;
;             const unsigned old = __hip_atomic_fetch_add(cnt + 64 * (1 + (blockIdx.x & 7)), 1u, __ATOMIC_RELAXED, __HIP_MEMORY_SCOPE_AGENT);
;             if (old + 1u == (G >> 3)) __hip_atomic_fetch_add(cnt, 1u, __ATOMIC_RELAXED, __HIP_MEMORY_SCOPE_AGENT); }
;         else { target = G; __hip_atomic_fetch_add(cnt, 1u, __ATOMIC_RELAXED, __HIP_MEMORY_SCOPE_AGENT); }
;         unsigned spins = 0;
;         while (__hip_atomic_load(cnt, __ATOMIC_RELAXED, __HIP_MEMORY_SCOPE_AGENT) < target && ++spins < (1u << 22)) __builtin_amdgcn_s_sleep(1);
;         __builtin_amdgcn_fence(__ATOMIC_ACQUIRE, "agent"); asm volatile("s_waitcnt vmcnt(0)" ::: "memory");
.LBB0_279:
	s_waitcnt vmcnt(0) lgkmcnt(0)
	v_cmp_eq_u32_e64 s[0:1], 0, v160
	v_cmp_ne_u32_e32 vcc, 0, v160
	s_waitcnt vmcnt(0)
	v_writelane_b32 v242, s0, 4
	s_barrier
	s_nop 0
	v_writelane_b32 v242, s1, 5
	s_and_saveexec_b64 s[0:1], vcc
	s_xor_b64 s[0:1], exec, s[0:1]
	s_and_b32 s4, s92, 7
	s_or_saveexec_b64 s[0:1], s[0:1]
	v_mov_b32_e32 v0, s4
	s_xor_b64 exec, exec, s[0:1]
	s_cbranch_execz .LBB0_301
	s_cmp_lg_u32 s92, 0x100
	s_cbranch_scc1 .Lseam1_orig
	buffer_wbl2 sc1
	s_waitcnt vmcnt(0)
	s_lshl_b32 s100, s2, 8
	s_and_b32 s100, s100, 0x700
	s_add_u32 s100, s100, 0x8e01100
	v_mov_b32_e32 v1, s100
	v_mov_b32_e32 v2, 1
	global_atomic_add v1, v2, s[90:91]
	s_mov_b64 exec, 0xff
	v_mbcnt_lo_u32_b32 v1, -1, 0
	v_lshlrev_b32_e32 v1, 8, v1
	v_add_u32_e32 v1, 0x8e01100, v1
	s_mov_b32 s100, 0x400000
.Lseam1_poll:
	global_load_dword v2, v1, s[90:91] sc1
	s_waitcnt vmcnt(0)
	v_cmp_gt_u32_e32 vcc, 32, v2
	s_cmp_eq_u64 vcc, 0
	s_cbranch_scc1 .Lseam1_done
	s_sleep 1
	s_add_i32 s100, s100, -1
	s_cmp_lg_u32 s100, 0
	s_cbranch_scc1 .Lseam1_poll
.Lseam1_done:
	s_mov_b64 exec, 1
	buffer_inv sc1
	s_waitcnt vmcnt(0)
	s_and_b32 s12, s92, 7
	s_branch .Lseam1_join
.Lseam1_orig:
	s_add_u32 s4, s90, 0x8e01000
	buffer_wbl2 sc1
	s_waitcnt vmcnt(0)
	s_addc_u32 s5, s91, 0
	s_and_b32 s12, s92, 7
	s_mov_b64 s[10:11], -1
	s_cmp_lg_u32 s12, 0
	s_mov_b32 s13, s92
	s_cbranch_scc0 .LBB0_284
	s_and_saveexec_b64 s[8:9], s[10:11]
	s_cbranch_execnz .LBB0_287
	s_branch .LBB0_289

; __device__ __forceinline__ void own_barrier(unsigned* cnt, unsigned G) {
;     ...
;         if ((G & 7u) == 0u) { target = 8u;
;             const unsigned old = __hip_atomic_fetch_add(cnt + 64 * (1 + (blockIdx.x & 7)), 1u, __ATOMIC_RELAXED, __HIP_MEMORY_SCOPE_AGENT);
;             if (old + 1u == (G >> 3)) __hip_atomic_fetch_add(cnt, 1u, __ATOMIC_RELAXED, __HIP_MEMORY_SCOPE_AGENT); }
;         else { target = G; __hip_atomic_fetch_add(cnt, 1u, __ATOMIC_RELAXED, __HIP_MEMORY_SCOPE_AGENT); }
.Lseam1_join:
	v_mov_b32_e32 v0, s12

; __device__ __forceinline__ void own_barrier(unsigned* cnt, unsigned G) {
;     asm volatile("s_waitcnt vmcnt(0) lgkmcnt(0)" ::: "memory");
;     __syncthreads();
;     if (threadIdx.x == 0) {
;         __builtin_amdgcn_fence(__ATOMIC_RELEASE, "agent"); asm volatile("s_waitcnt vmcnt(0)" ::: "memory");
;         unsigned target;
;         if ((G & 7u) == 0u) { target = 8u;
;             const unsigned old = __hip_atomic_fetch_add(cnt + 64 * (1 + (blockIdx.x & 7)), 1u, __ATOMIC_RELAXED, __HIP_MEMORY_SCOPE_AGENT);
;             if (old + 1u == (G >> 3)) __hip_atomic_fetch_add(cnt, 1u, __ATOMIC_RELAXED, __HIP_MEMORY_SCOPE_AGENT); }
;         else { target = G; __hip_atomic_fetch_add(cnt, 1u, __ATOMIC_RELAXED, __HIP_MEMORY_SCOPE_AGENT); }
;         unsigned spins = 0;
;         while (__hip_atomic_load(cnt, __ATOMIC_RELAXED, __HIP_MEMORY_SCOPE_AGENT) < target && ++spins < (1u << 22)) __builtin_amdgcn_s_sleep(1);
;         __builtin_amdgcn_fence(__ATOMIC_ACQUIRE, "agent"); asm volatile("s_waitcnt vmcnt(0)" ::: "memory");
.LBB0_340:
	s_waitcnt vmcnt(0) lgkmcnt(0)
	s_barrier
	s_mov_b64 s[4:5], exec
	v_readlane_b32 s8, v242, 4
	v_readlane_b32 s9, v242, 5
	s_and_b64 s[8:9], s[4:5], s[8:9]
	s_mov_b64 exec, s[8:9]
	s_cbranch_execz .LBB0_366
	s_cmp_lg_u32 s92, 0x100
	s_cbranch_scc1 .Lseam2_orig
	buffer_wbl2 sc1
	s_waitcnt vmcnt(0)
	s_lshl_b32 s100, s2, 8
	s_and_b32 s100, s100, 0x700
	s_add_u32 s100, s100, 0x8e02100
	v_mov_b32_e32 v1, s100
	v_mov_b32_e32 v2, 1
	global_atomic_add v1, v2, s[90:91]
	s_mov_b64 exec, 0xff
	v_mbcnt_lo_u32_b32 v1, -1, 0
	v_lshlrev_b32_e32 v1, 8, v1
	v_add_u32_e32 v1, 0x8e02100, v1
	s_mov_b32 s100, 0x400000

; __device__ __forceinline__ void own_barrier(unsigned* cnt, unsigned G) {
;     ...
;         __builtin_amdgcn_fence(__ATOMIC_RELEASE, "agent"); asm volatile("s_waitcnt vmcnt(0)" ::: "memory");
;         unsigned target;
;         if ((G & 7u) == 0u) { target = 8u;
;             const unsigned old = __hip_atomic_fetch_add(cnt + 64 * (1 + (blockIdx.x & 7)), 1u, __ATOMIC_RELAXED, __HIP_MEMORY_SCOPE_AGENT);
;             if (old + 1u == (G >> 3)) __hip_atomic_fetch_add(cnt, 1u, __ATOMIC_RELAXED, __HIP_MEMORY_SCOPE_AGENT); }
;         else { target = G; __hip_atomic_fetch_add(cnt, 1u, __ATOMIC_RELAXED, __HIP_MEMORY_SCOPE_AGENT); }
.Lseam2_done:
	s_mov_b64 exec, 1
	buffer_inv sc1
	s_waitcnt vmcnt(0)
	s_branch .Lseam2_join
.Lseam2_orig:
	buffer_wbl2 sc1
	s_waitcnt vmcnt(0)
	s_waitcnt vmcnt(0)
	s_add_u32 s8, s90, 0x8e02000
	s_addc_u32 s9, s91, 0
	s_mov_b64 s[12:13], -1
	v_mov_b32_e32 v0, s92
	s_and_saveexec_b64 s[10:11], s[60:61]
	s_cbranch_execz .LBB0_345
	s_mov_b64 s[14:15], exec
	v_mbcnt_lo_u32_b32 v0, s14, 0
	v_mbcnt_hi_u32_b32 v0, s15, v0
	v_cmp_eq_u32_e32 vcc, 0, v0
	s_and_saveexec_b64 s[12:13], vcc
	s_cbranch_execz .LBB0_344
	s_lshl_b32 s16, s2, 8
	s_and_b32 s16, s16, 0x700
	s_bcnt1_i32_b64 s14, s[14:15]
	v_mov_b32_e32 v1, s16
	v_mov_b32_e32 v2, s14
	global_atomic_add v1, v1, v2, s[8:9] offset:256 sc0

; __global__ void __launch_bounds__(512, 2) hybrid_fwd(Args a) {
;     ...
;         const int gw = bx * 8 + wave, NGW = G * 8;
;         const int hs = lane >> 4, dc = (lane & 15) * 8;
;         for (int t0 = gw; t0 < M; t0 += 2 * NGW) {
;             float lw[2][3]; u32x2 ov[2][3], gv[2]; int tt[2];
; #pragma unroll
;             for (int u = 0; u < 2; ++u) { const int t = (t0 + u * NGW < M) ? t0 + u * NGW : t0; tt[u] = t;
;                 const bf16_t* hp = H + (size_t)t * DIN;
; #pragma unroll
;                 for (int g3 = 0; g3 < 3; ++g3) { lw[u][g3] = LSE[((size_t)g3 * M + t) * 4 + hs]; ov[u][g3] = *(const u32x2*)((const unsigned char*)OG + ((size_t)g3 * M + t) * 512 + hs * 128 + dc); }
;                 gv[u] = *(const u32x2*)((const unsigned char*)(hp + OFF_GB) + hs * 128 + dc); }
.Lseam2_join:
.LBB0_366:
	s_or_b64 exec, exec, s[4:5]
	v_readlane_b32 s4, v242, 1
	s_cmpk_gt_i32 s4, 0x3fff
	s_barrier
	v_readlane_b32 s5, v242, 2
	s_cbranch_scc1 .LBB0_371
	v_readlane_b32 s4, v242, 6
	v_lshlrev_b32_e32 v12, 2, v139
	v_mov_b32_e32 v13, 0
	v_readlane_b32 s5, v242, 7
	v_lshlrev_b32_e32 v4, 7, v139
	v_mov_b32_e32 v5, v13
	v_lshl_add_u64 v[2:3], s[4:5], 0, v[12:13]
	v_readlane_b32 s4, v242, 1
	v_lshl_add_u64 v[6:7], s[0:1], 0, v[4:5]
	s_lshl_b32 s0, s92, 4
	s_mov_b32 s22, s4
	s_ashr_i32 s23, s4, 31
	s_mul_hi_i32 s1, s4, 0x600
	s_mulk_i32 s4, 0x600
	v_readlane_b32 s5, v242, 2
	s_add_u32 s4, s88, s4
	s_addc_u32 s5, s89, s1
	s_ashr_i32 s1, s0, 31
	s_lshl_b64 s[8:9], s[22:23], 4
	v_mov_b32_e32 v1, v13
	v_or_b32_e32 v12, s8, v12
	v_mov_b32_e32 v13, s9
	s_lshl_b64 s[8:9], s[0:1], 4
	s_lshl_b64 s[10:11], s[22:23], 9
	s_add_u32 s10, s88, s10
	s_addc_u32 s11, s89, s11
	v_lshl_add_u64 v[14:15], s[10:11], 0, v[4:5]
	s_lshl_b64 s[10:11], s[0:1], 9
	s_mul_hi_i32 s1, s22, 0x5a00
	s_mul_i32 s12, s22, 0x5a00
	v_and_b32_e32 v0, 0x78, v145
	v_lshl_add_u64 v[8:9], s[94:95], 0, v[4:5]
	v_lshl_add_u64 v[10:11], s[4:5], 0, v[4:5]
	s_mov_b64 s[4:5], 0x2000400
	v_or_b32_e32 v16, s12, v4
	v_mov_b32_e32 v17, s1
	s_mov_b64 s[12:13], 0x9003600
	s_mov_b32 s14, s22
	v_lshl_add_u64 v[6:7], v[6:7], 0, v[0:1]
	v_lshl_add_u64 v[8:9], v[8:9], 0, v[0:1]
	v_lshl_add_u64 v[10:11], v[10:11], 0, s[4:5]
	s_mul_i32 s4, s92, 0x6000
	s_mul_hi_i32 s5, s0, 0x600
	v_lshl_add_u64 v[16:17], v[16:17], 0, s[12:13]
	s_mul_i32 s12, s92, 0x5a000
	s_mul_hi_i32 s13, s0, 0x5a00
	v_lshl_add_u64 v[18:19], s[90:91], 0, v[0:1]
	s_movk_i32 s1, 0x3000
	s_mov_b32 s16, 0x4800000
	s_mov_b32 s17, 0x8880000
	s_brev_b32 s18, 32
	s_mov_b32 s19, 0x8840000
	s_mov_b32 s20, 0x3800000
	s_mov_b32 s21, 0x8800000
	v_mov_b32_e32 v28, 0x600
	v_writelane_b32 v242, s14, 1
	s_nop 1
	v_writelane_b32 v242, s15, 2
	s_branch .LBB0_369

; __device__ __forceinline__ void own_barrier(unsigned* cnt, unsigned G) {
;     asm volatile("s_waitcnt vmcnt(0) lgkmcnt(0)" ::: "memory");
;     __syncthreads();
;     if (threadIdx.x == 0) {
;         __builtin_amdgcn_fence(__ATOMIC_RELEASE, "agent"); asm volatile("s_waitcnt vmcnt(0)" ::: "memory");
;         unsigned target;
;         if ((G & 7u) == 0u) { target = 8u;
;             const unsigned old = __hip_atomic_fetch_add(cnt + 64 * (1 + (blockIdx.x & 7)), 1u, __ATOMIC_RELAXED, __HIP_MEMORY_SCOPE_AGENT);
;             if (old + 1u == (G >> 3)) __hip_atomic_fetch_add(cnt, 1u, __ATOMIC_RELAXED, __HIP_MEMORY_SCOPE_AGENT); }
;         else { target = G; __hip_atomic_fetch_add(cnt, 1u, __ATOMIC_RELAXED, __HIP_MEMORY_SCOPE_AGENT); }
;         unsigned spins = 0;
;         while (__hip_atomic_load(cnt, __ATOMIC_RELAXED, __HIP_MEMORY_SCOPE_AGENT) < target && ++spins < (1u << 22)) __builtin_amdgcn_s_sleep(1);
;         __builtin_amdgcn_fence(__ATOMIC_ACQUIRE, "agent"); asm volatile("s_waitcnt vmcnt(0)" ::: "memory");
.LBB0_371:
	s_waitcnt vmcnt(0) lgkmcnt(0)
	v_readlane_b32 s62, v242, 4
	v_readlane_b32 s63, v242, 5
	s_barrier
	s_and_saveexec_b64 s[0:1], s[62:63]
	s_cbranch_execz .LBB0_397
	s_cmp_lg_u32 s92, 0x100
	s_cbranch_scc1 .Lseam3_orig
	buffer_wbl2 sc1
	s_waitcnt vmcnt(0)
	s_lshl_b32 s100, s2, 8
	s_and_b32 s100, s100, 0x700
	s_add_u32 s100, s100, 0x8e03100
	v_mov_b32_e32 v1, s100
	v_mov_b32_e32 v2, 1
	global_atomic_add v1, v2, s[90:91]
	s_mov_b64 exec, 0xff
	v_mbcnt_lo_u32_b32 v1, -1, 0
	v_lshlrev_b32_e32 v1, 8, v1
	v_add_u32_e32 v1, 0x8e03100, v1
	s_mov_b32 s100, 0x400000

; __device__ __forceinline__ void own_barrier(unsigned* cnt, unsigned G) {
;     ...
;         __builtin_amdgcn_fence(__ATOMIC_RELEASE, "agent"); asm volatile("s_waitcnt vmcnt(0)" ::: "memory");
;         unsigned target;
;         if ((G & 7u) == 0u) { target = 8u;
;             const unsigned old = __hip_atomic_fetch_add(cnt + 64 * (1 + (blockIdx.x & 7)), 1u, __ATOMIC_RELAXED, __HIP_MEMORY_SCOPE_AGENT);
;             if (old + 1u == (G >> 3)) __hip_atomic_fetch_add(cnt, 1u, __ATOMIC_RELAXED, __HIP_MEMORY_SCOPE_AGENT); }
;         else { target = G; __hip_atomic_fetch_add(cnt, 1u, __ATOMIC_RELAXED, __HIP_MEMORY_SCOPE_AGENT); }
.Lseam3_orig:
	buffer_wbl2 sc1
	s_waitcnt vmcnt(0)
	s_waitcnt vmcnt(0)
	s_add_u32 s4, s90, 0x8e03000
	s_addc_u32 s5, s91, 0
	s_mov_b64 s[10:11], -1
	v_mov_b32_e32 v0, s92
	s_and_saveexec_b64 s[8:9], s[60:61]
	s_cbranch_execz .LBB0_376
	s_mov_b64 s[12:13], exec
	v_mbcnt_lo_u32_b32 v0, s12, 0
	v_mbcnt_hi_u32_b32 v0, s13, v0
	v_cmp_eq_u32_e32 vcc, 0, v0
	s_and_saveexec_b64 s[10:11], vcc
	s_cbranch_execz .LBB0_375
	s_lshl_b32 s14, s2, 8
	s_and_b32 s14, s14, 0x700
	s_bcnt1_i32_b64 s12, s[12:13]
	v_mov_b32_e32 v1, s14
	v_mov_b32_e32 v2, s12
	global_atomic_add v1, v1, v2, s[4:5] offset:256 sc0

; template <class Epi, class Sched, bool FP8 = false>
; __device__ __forceinline__ void gemm_phase(LAS unsigned char* lds, const Gemm g, const Sched& S, const Epi& E) {
;     const int tid = threadIdx.x;
;     const int wid = __builtin_amdgcn_readfirstlane(tid >> 6), lane = tid & 63, wr = wid >> 2, wc = wid & 3, fr = lane & 15, fq = lane >> 4;
;     unsigned voffA[2], voffB[2];
; #pragma unroll
;     for (int i = 0; i < 2; ++i) { int R, C; stage_rc(tid * 16 + i * 8192, R, C); const int Rb = Epi::PERM ? ((R & ~31) + perm32(R & 31)) : R;
;         voffA[i] = (unsigned)(R * g.lda + C) * 2u; voffB[i] = (unsigned)(Rb * g.ldb + C) * 2u; }
;     const size_t kstep = (size_t)(BK * 2);
;     const size_t hstepA = (size_t)HALF * g.lda * 2, hstepB = (size_t)HALF * g.ldb * 2;
;     const size_t tstepA = 2 * hstepA, tstepB = 2 * hstepB;
;     const unsigned ldsw = (unsigned)wid * 1024u;
;     const int aoff = lds_byte(wr * 64 + fr, fq * 8), boff = lds_byte(wc * 32 + fr, fq * 8);
.Lseam3_join:
.LBB0_397:
	s_or_b64 exec, exec, s[0:1]
	v_lshrrev_b32_e32 v0, 5, v160
	v_bfe_u32 v183, v160, 2, 4
	v_and_b32_e32 v8, 24, v131
	v_and_b32_e32 v0, 4, v0
	s_movk_i32 s0, 0x70
	v_or3_b32 v0, v0, v111, v8
	v_and_or_b32 v189, v108, s0, v183
	s_movk_i32 s0, 0x60
	v_add_u32_e32 v184, 0x2000, v109
	v_and_or_b32 v190, v108, s0, v0
	v_lshrrev_b32_e32 v1, 7, v184
	s_movk_i32 s0, 0xf0
	v_and_or_b32 v191, v1, s0, v183
	s_movk_i32 s0, 0xe0
	v_and_or_b32 v193, v1, s0, v0
	v_lshlrev_b32_e32 v0, 6, v160
	v_bitop3_b32 v157, v109, v162, 48 bitop3:0x6c
	v_and_b32_e32 v182, 64, v160
	v_and_b32_e32 v185, 0x3c0, v0
	v_lshlrev_b32_e32 v0, 2, v160
	s_cmpk_lt_i32 s2, 0x200
	v_readfirstlane_b32 s8, v160
	v_or_b32_e32 v188, v157, v182
	s_cselect_b64 s[0:1], -1, 0
	s_cmpk_gt_i32 s2, 0x1ff
	v_and_b32_e32 v187, 32, v0
	s_barrier
	s_cbranch_scc1 .LBB0_431
	s_lshr_b32 s4, s3, 29
	s_add_i32 s10, s2, s4
	s_and_b32 s4, s10, -8
	s_sub_i32 s9, s2, s4
	s_cmp_gt_i32 s9, -1
	s_cbranch_scc0 .LBB0_400
	s_lshl_b32 s12, s9, 6
	s_cbranch_execz .LBB0_401
	s_branch .LBB0_402

; __device__ __forceinline__ void own_barrier(unsigned* cnt, unsigned G) {
;     asm volatile("s_waitcnt vmcnt(0) lgkmcnt(0)" ::: "memory");
;     __syncthreads();
;     if (threadIdx.x == 0) {
;         __builtin_amdgcn_fence(__ATOMIC_RELEASE, "agent"); asm volatile("s_waitcnt vmcnt(0)" ::: "memory");
;         unsigned target;
;         if ((G & 7u) == 0u) { target = 8u;
;             const unsigned old = __hip_atomic_fetch_add(cnt + 64 * (1 + (blockIdx.x & 7)), 1u, __ATOMIC_RELAXED, __HIP_MEMORY_SCOPE_AGENT);
;             if (old + 1u == (G >> 3)) __hip_atomic_fetch_add(cnt, 1u, __ATOMIC_RELAXED, __HIP_MEMORY_SCOPE_AGENT); }
;         else { target = G; __hip_atomic_fetch_add(cnt, 1u, __ATOMIC_RELAXED, __HIP_MEMORY_SCOPE_AGENT); }
;         unsigned spins = 0;
;         while (__hip_atomic_load(cnt, __ATOMIC_RELAXED, __HIP_MEMORY_SCOPE_AGENT) < target && ++spins < (1u << 22)) __builtin_amdgcn_s_sleep(1);
;         __builtin_amdgcn_fence(__ATOMIC_ACQUIRE, "agent"); asm volatile("s_waitcnt vmcnt(0)" ::: "memory");
.LBB0_431:
	s_waitcnt vmcnt(0) lgkmcnt(0)
	s_waitcnt vmcnt(0)
	s_barrier
	s_and_saveexec_b64 s[4:5], s[62:63]
	s_cbranch_execz .LBB0_457
	s_cmp_lg_u32 s92, 0x100
	s_cbranch_scc1 .Lseam4_orig
	buffer_wbl2 sc1
	s_waitcnt vmcnt(0)
	s_lshl_b32 s100, s2, 8
	s_and_b32 s100, s100, 0x700
	s_add_u32 s100, s100, 0x8e04100
	v_mov_b32_e32 v1, s100
	v_mov_b32_e32 v2, 1
	global_atomic_add v1, v2, s[90:91]
	s_mov_b64 exec, 0xff
	v_mbcnt_lo_u32_b32 v1, -1, 0
	v_lshlrev_b32_e32 v1, 8, v1
	v_add_u32_e32 v1, 0x8e04100, v1
	s_mov_b32 s100, 0x400000

; __device__ __forceinline__ void own_barrier(unsigned* cnt, unsigned G) {
;     ...
;         __builtin_amdgcn_fence(__ATOMIC_RELEASE, "agent"); asm volatile("s_waitcnt vmcnt(0)" ::: "memory");
;         unsigned target;
;         if ((G & 7u) == 0u) { target = 8u;
;             const unsigned old = __hip_atomic_fetch_add(cnt + 64 * (1 + (blockIdx.x & 7)), 1u, __ATOMIC_RELAXED, __HIP_MEMORY_SCOPE_AGENT);
;             if (old + 1u == (G >> 3)) __hip_atomic_fetch_add(cnt, 1u, __ATOMIC_RELAXED, __HIP_MEMORY_SCOPE_AGENT); }
;         else { target = G; __hip_atomic_fetch_add(cnt, 1u, __ATOMIC_RELAXED, __HIP_MEMORY_SCOPE_AGENT); }
.Lseam4_orig:
	buffer_wbl2 sc1
	s_waitcnt vmcnt(0)
	s_add_u32 s6, s90, 0x8e04000
	s_addc_u32 s7, s91, 0
	s_mov_b64 s[10:11], -1
	v_mov_b32_e32 v0, s92
	s_and_saveexec_b64 s[8:9], s[60:61]
	s_cbranch_execz .LBB0_436
	s_mov_b64 s[12:13], exec
	v_mbcnt_lo_u32_b32 v0, s12, 0
	v_mbcnt_hi_u32_b32 v0, s13, v0
	v_cmp_eq_u32_e32 vcc, 0, v0
	s_and_saveexec_b64 s[10:11], vcc
	s_cbranch_execz .LBB0_435
	s_lshl_b32 s14, s2, 8
	s_and_b32 s14, s14, 0x700
	s_bcnt1_i32_b64 s12, s[12:13]
	v_mov_b32_e32 v1, s14
	v_mov_b32_e32 v2, s12
	global_atomic_add v1, v1, v2, s[6:7] offset:256 sc0

; __global__ void __launch_bounds__(512, 2) hybrid_fwd(Args a) {
;     ...
;     {
;         pg8::Gemm g{(const bf16_t*)MG8, (const bf16_t*)Wout8, D / 2, D / 2}; pg8::OrderPlain S{M / 256, D / 256, (M / 256) * (D / 256), G, bx, D / 128};
;         Epi3 E{a.x, Z16, STATS, 1.0f / (SM8 * W8_SCALE)};
;         pg8::gemm_phase<Epi3, pg8::OrderPlain, true>(lds, g, S, E);
.Lseam4_join:
.LBB0_457:
	s_or_b64 exec, exec, s[4:5]
	s_load_dwordx2 s[4:5], s[70:71], 0x0
	v_cndmask_b32_e64 v0, 0, 1, s[0:1]
	v_cmp_ne_u32_e64 s[8:9], 1, v0
	s_andn2_b64 vcc, exec, s[0:1]
	v_readfirstlane_b32 s10, v160
	s_waitcnt lgkmcnt(0)
	s_barrier
	s_cbranch_vccnz .LBB0_463
	s_lshr_b32 s0, s3, 29
	s_add_i32 s11, s2, s0
	s_and_b32 s0, s11, -8
	s_sub_i32 s6, s2, s0
	s_cmp_gt_i32 s6, -1
	s_cbranch_scc0 .LBB0_460
	s_lshl_b32 s7, s6, 6
	s_ashr_i32 s0, s11, 3
	s_cbranch_execz .LBB0_461
	s_branch .LBB0_462

; __device__ __forceinline__ void own_barrier(unsigned* cnt, unsigned G) {
;     asm volatile("s_waitcnt vmcnt(0) lgkmcnt(0)" ::: "memory");
;     __syncthreads();
;     if (threadIdx.x == 0) {
;         __builtin_amdgcn_fence(__ATOMIC_RELEASE, "agent"); asm volatile("s_waitcnt vmcnt(0)" ::: "memory");
;         unsigned target;
;         if ((G & 7u) == 0u) { target = 8u;
;             const unsigned old = __hip_atomic_fetch_add(cnt + 64 * (1 + (blockIdx.x & 7)), 1u, __ATOMIC_RELAXED, __HIP_MEMORY_SCOPE_AGENT);
;             if (old + 1u == (G >> 3)) __hip_atomic_fetch_add(cnt, 1u, __ATOMIC_RELAXED, __HIP_MEMORY_SCOPE_AGENT); }
;         else { target = G; __hip_atomic_fetch_add(cnt, 1u, __ATOMIC_RELAXED, __HIP_MEMORY_SCOPE_AGENT); }
;         unsigned spins = 0;
;         while (__hip_atomic_load(cnt, __ATOMIC_RELAXED, __HIP_MEMORY_SCOPE_AGENT) < target && ++spins < (1u << 22)) __builtin_amdgcn_s_sleep(1);
;         __builtin_amdgcn_fence(__ATOMIC_ACQUIRE, "agent"); asm volatile("s_waitcnt vmcnt(0)" ::: "memory");
.LBB0_499:
	s_waitcnt vmcnt(0) lgkmcnt(0)
	s_waitcnt lgkmcnt(0)
	s_barrier
	s_and_saveexec_b64 s[4:5], s[62:63]
	s_cbranch_execz .LBB0_525
	s_cmp_lg_u32 s92, 0x100
	s_cbranch_scc1 .Lseam5_orig
	buffer_wbl2 sc1
	s_waitcnt vmcnt(0)
	s_lshl_b32 s100, s2, 8
	s_and_b32 s100, s100, 0x700
	s_add_u32 s100, s100, 0x8e05100
	v_mov_b32_e32 v1, s100
	v_mov_b32_e32 v2, 1
	global_atomic_add v1, v2, s[90:91]
	s_mov_b64 exec, 0xff
	v_mbcnt_lo_u32_b32 v1, -1, 0
	v_lshlrev_b32_e32 v1, 8, v1
	v_add_u32_e32 v1, 0x8e05100, v1
	s_mov_b32 s100, 0x400000

; __device__ __forceinline__ void own_barrier(unsigned* cnt, unsigned G) {
;     ...
;         __builtin_amdgcn_fence(__ATOMIC_RELEASE, "agent"); asm volatile("s_waitcnt vmcnt(0)" ::: "memory");
;         unsigned target;
;         if ((G & 7u) == 0u) { target = 8u;
;             const unsigned old = __hip_atomic_fetch_add(cnt + 64 * (1 + (blockIdx.x & 7)), 1u, __ATOMIC_RELAXED, __HIP_MEMORY_SCOPE_AGENT);
;             if (old + 1u == (G >> 3)) __hip_atomic_fetch_add(cnt, 1u, __ATOMIC_RELAXED, __HIP_MEMORY_SCOPE_AGENT); }
;         else { target = G; __hip_atomic_fetch_add(cnt, 1u, __ATOMIC_RELAXED, __HIP_MEMORY_SCOPE_AGENT); }
.Lseam5_orig:
	buffer_wbl2 sc1
	s_waitcnt vmcnt(0)
	s_waitcnt vmcnt(0)
	s_add_u32 s6, s90, 0x8e05000
	s_addc_u32 s7, s91, 0
	s_mov_b64 s[10:11], -1
	v_mov_b32_e32 v0, s92
	s_and_saveexec_b64 s[8:9], s[60:61]
	s_cbranch_execz .LBB0_504
	s_mov_b64 s[12:13], exec
	v_mbcnt_lo_u32_b32 v0, s12, 0
	v_mbcnt_hi_u32_b32 v0, s13, v0
	v_cmp_eq_u32_e32 vcc, 0, v0
	s_and_saveexec_b64 s[10:11], vcc
	s_cbranch_execz .LBB0_503
	s_lshl_b32 s3, s2, 8
	s_and_b32 s3, s3, 0x700
	s_bcnt1_i32_b64 s12, s[12:13]
	v_mov_b32_e32 v1, s3
	v_mov_b32_e32 v2, s12
	global_atomic_add v1, v1, v2, s[6:7] offset:256 sc0

; __global__ void __launch_bounds__(512, 2) hybrid_fwd(Args a) {
;     ...
;         const int xcd = bx & 7, cu_in_x = bx >> 3, per_x = G >> 3;
;         const int gw = (G % 8 == 0) ? (cu_in_x * 8 + wave) : (bx * 8 + wave), NGW = (G % 8 == 0) ? per_x * 8 : G * 8;
;         const int row_base = (G % 8 == 0) ? xcd * (M / 8) : 0, row_cnt = (G % 8 == 0) ? (M / 8) : M;
;         typedef _Float16 h8 __attribute__((ext_vector_type(8)));
;         for (int tl = gw; tl < row_cnt; tl += 8 * NGW) {
;             int tr[8]; f32x2 pr[8]; h8 zz[8][4];
; #pragma unroll
;             for (int u = 0; u < 8; ++u) { tr[u] = (tl + u * NGW < row_cnt) ? row_base + tl + u * NGW : row_base + tl;
;                 pr[u] = (lane < 32) ? STATS[(size_t)tr[u] * 32 + lane] : (f32x2){0.f, 0.f};
; #pragma unroll
;                 for (int j = 0; j < 4; ++j) zz[u][j] = *(const h8*)(Z16 + (size_t)tr[u] * D + 512 * j + 8 * lane); }
; #pragma unroll
;             for (int u = 0; u < 8; ++u) {
;                 float s0 = pr[u].x, q0 = pr[u].y;
; #pragma unroll
;                 for (int o = 1; o < 64; o <<= 1) { s0 += __shfl_xor(s0, o); q0 += __shfl_xor(q0, o); }
.Lseam5_join:
.LBB0_525:
	s_or_b64 exec, exec, s[4:5]
	s_and_b32 s2, s2, -8
	v_readlane_b32 s3, v242, 0
	s_add_i32 s2, s3, s2
	v_readlane_b32 s4, v242, 1
	v_mov_b32_e32 v1, s2
	s_nop 0
	v_mov_b32_e32 v0, s4
	v_cndmask_b32_e64 v8, v0, v1, s[60:61]
	v_mov_b32_e32 v0, 0x4000
	v_mov_b32_e32 v1, 0x800
	v_cndmask_b32_e64 v173, v0, v1, s[60:61]
	v_cmp_lt_i32_e32 vcc, v8, v173
	s_barrier
	v_readlane_b32 s5, v242, 2
	s_and_saveexec_b64 s[2:3], vcc
	s_cbranch_execz .LBB0_558
	v_mov_b32_e32 v0, s72
	v_mov_b32_e32 v1, s92
	s_lshl_b32 s2, s59, 11
	v_cndmask_b32_e64 v174, v0, v1, s[60:61]
	v_mov_b32_e32 v0, s2
	v_cndmask_b32_e64 v175, 0, v0, s[60:61]
	v_lshlrev_b32_e32 v0, 3, v192
	v_mov_b32_e32 v1, 0
	v_lshl_add_u64 v[126:127], s[0:1], 0, v[0:1]
	s_load_dwordx4 s[4:7], s[70:71], 0x40
	s_load_dwordx2 s[0:1], s[70:71], 0x50
	v_lshlrev_b32_e32 v2, 4, v192
	v_mov_b32_e32 v3, v1
	v_lshl_add_u64 v[124:125], s[96:97], 0, v[2:3]
	v_mbcnt_hi_u32_b32 v2, -1, v186
	v_and_b32_e32 v0, 64, v2
	v_add_u32_e32 v3, 64, v0
	v_lshlrev_b32_e32 v0, 5, v192
	s_waitcnt lgkmcnt(0)
	v_lshl_add_u64 v[128:129], s[0:1], 0, v[0:1]
	v_lshl_add_u64 v[130:131], s[4:5], 0, v[0:1]
	v_lshl_add_u64 v[132:133], s[6:7], 0, v[0:1]
	v_xor_b32_e32 v0, 1, v2
	v_cmp_lt_i32_e32 vcc, v0, v3
	s_mov_b64 s[0:1], 0x1000
	v_lshl_add_u64 v[134:135], v[130:131], 0, s[0:1]
	v_cndmask_b32_e32 v0, v2, v0, vcc
	v_lshlrev_b32_e32 v182, 2, v0
	v_xor_b32_e32 v0, 2, v2
	v_cmp_lt_i32_e32 vcc, v0, v3
	v_lshl_add_u64 v[136:137], v[132:133], 0, s[0:1]
	s_mov_b64 s[0:1], 0x1800
	v_cndmask_b32_e32 v0, v2, v0, vcc
	v_lshlrev_b32_e32 v183, 2, v0
	v_xor_b32_e32 v0, 4, v2
	v_cmp_lt_i32_e32 vcc, v0, v3
	v_cmp_gt_u32_e64 s[2:3], 32, v192
	v_lshlrev_b32_e32 v176, 1, v174
	v_cndmask_b32_e32 v0, v2, v0, vcc
	v_lshlrev_b32_e32 v184, 2, v0
	v_xor_b32_e32 v0, 8, v2
	v_cmp_lt_i32_e32 vcc, v0, v3
	v_lshl_add_u32 v177, v174, 1, v174
	v_lshlrev_b32_e32 v178, 2, v174
	v_cndmask_b32_e32 v0, v2, v0, vcc
	v_lshlrev_b32_e32 v185, 2, v0
	v_xor_b32_e32 v0, 16, v2
	v_cmp_lt_i32_e32 vcc, v0, v3
	v_lshl_add_u32 v179, v174, 2, v174
	v_mul_lo_u32 v180, v174, 6
	v_cndmask_b32_e32 v0, v2, v0, vcc
	v_lshlrev_b32_e32 v186, 2, v0
	v_xor_b32_e32 v0, 32, v2
	v_cmp_lt_i32_e32 vcc, v0, v3
	v_mul_lo_u32 v181, v174, 7
	v_lshl_add_u64 v[138:139], v[130:131], 0, s[0:1]
	v_cndmask_b32_e32 v0, v2, v0, vcc
	v_lshlrev_b32_e32 v187, 2, v0
	v_lshl_add_u64 v[140:141], v[132:133], 0, s[0:1]
	s_mov_b64 s[4:5], 0
	s_mov_b32 s6, 0x3a000000
	s_mov_b32 s7, 0xf800000
	v_mov_b32_e32 v188, 0x260
	s_movk_i32 s10, 0x1000
	s_branch .LBB0_528
